# attention: static s_setprio 1 for waves 4-7 during the attention item loop
# speedup vs baseline: 1.0059x; 1.0059x over previous
.LBB0_604:
	s_setprio 0
	s_waitcnt vmcnt(0)
	s_barrier
	s_and_saveexec_b64 s[0:1], s[58:59]
	v_readlane_b32 s36, v248, 20
	v_readlane_b32 s19, v248, 11
	v_readlane_b32 s37, v248, 21
	s_cbranch_execz .LBB0_693
	v_readlane_b32 s3, v248, 3
	s_waitcnt vmcnt(0) expcnt(0) lgkmcnt(0)
	s_nop 0
	v_mov_b32_e32 v0, s3
	ds_read_b32 v2, v0
	v_readlane_b32 s3, v248, 4
	s_waitcnt lgkmcnt(0)
	v_cmp_ne_u32_e32 vcc, 0, v2
	v_mov_b32_e32 v0, s3
	ds_read_b32 v0, v0
	s_cbranch_vccnz .LBB0_640
	s_mov_b32 s3, 1
	s_branch .LBB0_628

.LBB0_608:
	v_readfirstlane_b32 s0, v188
	s_nop 3
	s_cmpk_lt_u32 s0, 0x100
	s_cbranch_scc1 .Latt_noprio
	s_setprio 1
